# v114 + RWKV scanner v6: the first step of each chunk uses counted lgkmcnt waits (starts on the first array instead of waiting for all 12 initial LDS loads)
# speedup vs baseline: 1.0070x; 1.0043x over previous
.Lscan_chunk:
	v_add_u32_e32 v130, s1, v137
	v_add_u32_e32 v131, s1, v139
	v_add_u32_e32 v85, s1, v156
	v_add_u32_e32 v86, s1, v84
	s_mov_b32 s0, 4
	ds_read_b128 v[32:35], v130 offset:0
	ds_read_b128 v[36:39], v130 offset:16
	ds_read_b128 v[40:43], v130 offset:4096
	ds_read_b128 v[44:47], v130 offset:4112
	ds_read_b128 v[56:59], v130 offset:12288
	ds_read_b128 v[60:63], v130 offset:12304
	ds_read_b128 v[64:67], v130 offset:16384
	ds_read_b128 v[68:71], v130 offset:16400
	ds_read_b128 v[48:51], v130 offset:8192
	ds_read_b128 v[52:55], v130 offset:8208
	ds_read2_b64 v[72:75], v131 offset0:0 offset1:32
	ds_read2_b64 v[140:143], v85 offset0:0 offset1:2
	s_waitcnt lgkmcnt(10)
	v_pk_mul_f32 v[16:17], v[2:3], v[34:35]
	v_pk_mul_f32 v[18:19], v[10:11], v[34:35]
	ds_read_b128 v[76:79], v130 offset:256
	v_pk_fma_f32 v[16:17], v[0:1], v[32:33], v[16:17]
	v_pk_fma_f32 v[18:19], v[8:9], v[32:33], v[18:19]
	ds_read_b128 v[80:83], v130 offset:272
	v_pk_fma_f32 v[16:17], v[4:5], v[36:37], v[16:17]
	v_pk_fma_f32 v[18:19], v[12:13], v[36:37], v[18:19]
	ds_read_b128 v[90:93], v130 offset:4352
	v_pk_fma_f32 v[16:17], v[6:7], v[38:39], v[16:17]
	v_pk_fma_f32 v[18:19], v[14:15], v[38:39], v[18:19]
	ds_read_b128 v[94:97], v130 offset:4368
	s_waitcnt lgkmcnt(12)
	v_pk_mul_f32 v[20:21], v[2:3], v[42:43]
	v_add_f32_e32 v24, v16, v17
	ds_read_b128 v[112:115], v130 offset:12544
	v_add_f32_e32 v25, v18, v19
	v_pk_mul_f32 v[22:23], v[10:11], v[42:43]
	ds_read_b128 v[116:119], v130 offset:12560
	v_add_f32_dpp v24, v24, v24 quad_perm:[1,0,3,2] row_mask:0xf bank_mask:0xf bound_ctrl:1
	v_add_f32_dpp v25, v25, v25 quad_perm:[1,0,3,2] row_mask:0xf bank_mask:0xf bound_ctrl:1
	ds_read_b128 v[120:123], v130 offset:16640
	v_pk_fma_f32 v[20:21], v[0:1], v[40:41], v[20:21]
	v_add_f32_dpp v24, v24, v24 quad_perm:[2,3,0,1] row_mask:0xf bank_mask:0xf bound_ctrl:1
	ds_read_b128 v[124:127], v130 offset:16656
	v_add_f32_dpp v25, v25, v25 quad_perm:[2,3,0,1] row_mask:0xf bank_mask:0xf bound_ctrl:1
	v_pk_fma_f32 v[22:23], v[8:9], v[40:41], v[22:23]
	ds_read_b128 v[98:101], v130 offset:8448
	v_add_f32_dpp v24, v24, v24 row_half_mirror row_mask:0xf bank_mask:0xf bound_ctrl:1
	v_add_f32_dpp v25, v25, v25 row_half_mirror row_mask:0xf bank_mask:0xf bound_ctrl:1
	ds_read_b128 v[102:105], v130 offset:8464
	v_pk_fma_f32 v[20:21], v[4:5], v[44:45], v[20:21]
	v_pk_fma_f32 v[22:23], v[12:13], v[44:45], v[22:23]
	ds_read2_b64 v[106:109], v131 offset0:64 offset1:96
	v_pk_fma_f32 v[20:21], v[6:7], v[46:47], v[20:21]
	v_pk_fma_f32 v[22:23], v[14:15], v[46:47], v[22:23]
	ds_read2_b64 v[144:147], v85 offset0:4 offset1:6
	s_waitcnt lgkmcnt(12)
	v_add_f32_e32 v26, v20, v21
	v_add_f32_e32 v27, v22, v23
	v_pk_fma_f32 v[176:177], v[24:25], v[140:141], v[26:27] op_sel_hi:[1,0,1]
	v_pk_mul_f32 v[164:165], v[56:57], v[24:25] op_sel_hi:[1,0]
	v_pk_mul_f32 v[166:167], v[56:57], v[24:25] op_sel:[0,1]
	v_pk_mul_f32 v[168:169], v[58:59], v[24:25] op_sel_hi:[1,0]
	v_pk_mul_f32 v[170:171], v[58:59], v[24:25] op_sel:[0,1]
	v_pk_fma_f32 v[164:165], v[64:65], v[72:73], v[164:165] op_sel_hi:[1,0,1]
	v_pk_fma_f32 v[166:167], v[64:65], v[72:73], v[166:167] op_sel:[0,1,0]
	v_pk_fma_f32 v[168:169], v[66:67], v[72:73], v[168:169] op_sel_hi:[1,0,1]
	v_pk_fma_f32 v[170:171], v[66:67], v[72:73], v[170:171] op_sel:[0,1,0]
	v_pk_fma_f32 v[0:1], v[0:1], v[48:49], v[164:165]
	v_pk_fma_f32 v[8:9], v[8:9], v[48:49], v[166:167]
	v_pk_fma_f32 v[2:3], v[2:3], v[50:51], v[168:169]
	v_pk_fma_f32 v[10:11], v[10:11], v[50:51], v[170:171]
	v_pk_mul_f32 v[164:165], v[60:61], v[24:25] op_sel_hi:[1,0]
	v_pk_mul_f32 v[166:167], v[60:61], v[24:25] op_sel:[0,1]
	v_pk_mul_f32 v[168:169], v[62:63], v[24:25] op_sel_hi:[1,0]
	v_pk_mul_f32 v[170:171], v[62:63], v[24:25] op_sel:[0,1]
	v_pk_fma_f32 v[164:165], v[68:69], v[72:73], v[164:165] op_sel_hi:[1,0,1]
	v_pk_fma_f32 v[166:167], v[68:69], v[72:73], v[166:167] op_sel:[0,1,0]
	v_pk_fma_f32 v[168:169], v[70:71], v[72:73], v[168:169] op_sel_hi:[1,0,1]
	v_pk_fma_f32 v[170:171], v[70:71], v[72:73], v[170:171] op_sel:[0,1,0]
	v_pk_fma_f32 v[4:5], v[4:5], v[52:53], v[164:165]
	v_pk_fma_f32 v[12:13], v[12:13], v[52:53], v[166:167]
	v_pk_fma_f32 v[6:7], v[6:7], v[54:55], v[168:169]
	v_pk_fma_f32 v[14:15], v[14:15], v[54:55], v[170:171]
	v_pk_fma_f32 v[176:177], v[72:73], v[140:141], v[176:177] op_sel:[0,1,0]
	s_branch .Lscan_q4b
.Lscan_q4:
	s_waitcnt lgkmcnt(0)
	v_pk_mul_f32 v[16:17], v[2:3], v[34:35]
	v_pk_mul_f32 v[18:19], v[10:11], v[34:35]
	ds_read_b128 v[76:79], v130 offset:256
	v_pk_fma_f32 v[16:17], v[0:1], v[32:33], v[16:17]
	v_pk_fma_f32 v[18:19], v[8:9], v[32:33], v[18:19]
	ds_read_b128 v[80:83], v130 offset:272
	v_pk_fma_f32 v[16:17], v[4:5], v[36:37], v[16:17]
	v_pk_fma_f32 v[18:19], v[12:13], v[36:37], v[18:19]
	ds_read_b128 v[90:93], v130 offset:4352
	v_pk_fma_f32 v[16:17], v[6:7], v[38:39], v[16:17]
	v_pk_fma_f32 v[18:19], v[14:15], v[38:39], v[18:19]
	ds_read_b128 v[94:97], v130 offset:4368
	v_pk_mul_f32 v[20:21], v[2:3], v[42:43]
	v_add_f32_e32 v24, v16, v17
	ds_read_b128 v[112:115], v130 offset:12544
	v_add_f32_e32 v25, v18, v19
	v_pk_mul_f32 v[22:23], v[10:11], v[42:43]
	ds_read_b128 v[116:119], v130 offset:12560
	v_add_f32_dpp v24, v24, v24 quad_perm:[1,0,3,2] row_mask:0xf bank_mask:0xf bound_ctrl:1
	v_add_f32_dpp v25, v25, v25 quad_perm:[1,0,3,2] row_mask:0xf bank_mask:0xf bound_ctrl:1
	ds_read_b128 v[120:123], v130 offset:16640
	v_pk_fma_f32 v[20:21], v[0:1], v[40:41], v[20:21]
	v_add_f32_dpp v24, v24, v24 quad_perm:[2,3,0,1] row_mask:0xf bank_mask:0xf bound_ctrl:1
	ds_read_b128 v[124:127], v130 offset:16656
	v_add_f32_dpp v25, v25, v25 quad_perm:[2,3,0,1] row_mask:0xf bank_mask:0xf bound_ctrl:1
	v_pk_fma_f32 v[22:23], v[8:9], v[40:41], v[22:23]
	ds_read_b128 v[98:101], v130 offset:8448
	v_add_f32_dpp v24, v24, v24 row_half_mirror row_mask:0xf bank_mask:0xf bound_ctrl:1
	v_add_f32_dpp v25, v25, v25 row_half_mirror row_mask:0xf bank_mask:0xf bound_ctrl:1
	ds_read_b128 v[102:105], v130 offset:8464
	v_pk_fma_f32 v[20:21], v[4:5], v[44:45], v[20:21]
	v_pk_fma_f32 v[22:23], v[12:13], v[44:45], v[22:23]
	ds_read2_b64 v[106:109], v131 offset0:64 offset1:96
	v_pk_fma_f32 v[20:21], v[6:7], v[46:47], v[20:21]
	v_pk_fma_f32 v[22:23], v[14:15], v[46:47], v[22:23]
	ds_read2_b64 v[144:147], v85 offset0:4 offset1:6
	v_add_f32_e32 v26, v20, v21
	v_add_f32_e32 v27, v22, v23
	v_pk_fma_f32 v[176:177], v[24:25], v[140:141], v[26:27] op_sel_hi:[1,0,1]
	v_pk_mul_f32 v[164:165], v[56:57], v[24:25] op_sel_hi:[1,0]
	v_pk_mul_f32 v[166:167], v[56:57], v[24:25] op_sel:[0,1]
	v_pk_mul_f32 v[168:169], v[58:59], v[24:25] op_sel_hi:[1,0]
	v_pk_mul_f32 v[170:171], v[58:59], v[24:25] op_sel:[0,1]
	v_pk_fma_f32 v[164:165], v[64:65], v[72:73], v[164:165] op_sel_hi:[1,0,1]
	v_pk_fma_f32 v[166:167], v[64:65], v[72:73], v[166:167] op_sel:[0,1,0]
	v_pk_fma_f32 v[168:169], v[66:67], v[72:73], v[168:169] op_sel_hi:[1,0,1]
	v_pk_fma_f32 v[170:171], v[66:67], v[72:73], v[170:171] op_sel:[0,1,0]
	v_pk_fma_f32 v[0:1], v[0:1], v[48:49], v[164:165]
	v_pk_fma_f32 v[8:9], v[8:9], v[48:49], v[166:167]
	v_pk_fma_f32 v[2:3], v[2:3], v[50:51], v[168:169]
	v_pk_fma_f32 v[10:11], v[10:11], v[50:51], v[170:171]
	v_pk_mul_f32 v[164:165], v[60:61], v[24:25] op_sel_hi:[1,0]
	v_pk_mul_f32 v[166:167], v[60:61], v[24:25] op_sel:[0,1]
	v_pk_mul_f32 v[168:169], v[62:63], v[24:25] op_sel_hi:[1,0]
	v_pk_mul_f32 v[170:171], v[62:63], v[24:25] op_sel:[0,1]
	v_pk_fma_f32 v[164:165], v[68:69], v[72:73], v[164:165] op_sel_hi:[1,0,1]
	v_pk_fma_f32 v[166:167], v[68:69], v[72:73], v[166:167] op_sel:[0,1,0]
	v_pk_fma_f32 v[168:169], v[70:71], v[72:73], v[168:169] op_sel_hi:[1,0,1]
	v_pk_fma_f32 v[170:171], v[70:71], v[72:73], v[170:171] op_sel:[0,1,0]
	v_pk_fma_f32 v[4:5], v[4:5], v[52:53], v[164:165]
	v_pk_fma_f32 v[12:13], v[12:13], v[52:53], v[166:167]
	v_pk_fma_f32 v[6:7], v[6:7], v[54:55], v[168:169]
	v_pk_fma_f32 v[14:15], v[14:15], v[54:55], v[170:171]
	v_pk_fma_f32 v[176:177], v[72:73], v[140:141], v[176:177] op_sel:[0,1,0]
.Lscan_q4b:
	s_waitcnt lgkmcnt(0)
	v_pk_mul_f32 v[16:17], v[2:3], v[78:79]
	v_pk_mul_f32 v[18:19], v[10:11], v[78:79]
	ds_read_b128 v[32:35], v130 offset:512
	v_pk_fma_f32 v[16:17], v[0:1], v[76:77], v[16:17]
	v_pk_fma_f32 v[18:19], v[8:9], v[76:77], v[18:19]
	ds_read_b128 v[36:39], v130 offset:528
	v_pk_fma_f32 v[16:17], v[4:5], v[80:81], v[16:17]
	v_pk_fma_f32 v[18:19], v[12:13], v[80:81], v[18:19]
	ds_read_b128 v[40:43], v130 offset:4608
	v_pk_fma_f32 v[16:17], v[6:7], v[82:83], v[16:17]
	v_pk_fma_f32 v[18:19], v[14:15], v[82:83], v[18:19]
	ds_read_b128 v[44:47], v130 offset:4624
	v_pk_mul_f32 v[20:21], v[2:3], v[92:93]
	v_add_f32_e32 v24, v16, v17
	ds_read_b128 v[56:59], v130 offset:12800
	v_add_f32_e32 v25, v18, v19
	v_pk_mul_f32 v[22:23], v[10:11], v[92:93]
	ds_read_b128 v[60:63], v130 offset:12816
	v_add_f32_dpp v24, v24, v24 quad_perm:[1,0,3,2] row_mask:0xf bank_mask:0xf bound_ctrl:1
	v_add_f32_dpp v25, v25, v25 quad_perm:[1,0,3,2] row_mask:0xf bank_mask:0xf bound_ctrl:1
	ds_read_b128 v[64:67], v130 offset:16896
	v_pk_fma_f32 v[20:21], v[0:1], v[90:91], v[20:21]
	v_add_f32_dpp v24, v24, v24 quad_perm:[2,3,0,1] row_mask:0xf bank_mask:0xf bound_ctrl:1
	ds_read_b128 v[68:71], v130 offset:16912
	v_add_f32_dpp v25, v25, v25 quad_perm:[2,3,0,1] row_mask:0xf bank_mask:0xf bound_ctrl:1
	v_pk_fma_f32 v[22:23], v[8:9], v[90:91], v[22:23]
	ds_read_b128 v[48:51], v130 offset:8704
	v_add_f32_dpp v24, v24, v24 row_half_mirror row_mask:0xf bank_mask:0xf bound_ctrl:1
	v_add_f32_dpp v25, v25, v25 row_half_mirror row_mask:0xf bank_mask:0xf bound_ctrl:1
	ds_read_b128 v[52:55], v130 offset:8720
	v_pk_fma_f32 v[20:21], v[4:5], v[94:95], v[20:21]
	v_pk_fma_f32 v[22:23], v[12:13], v[94:95], v[22:23]
	v_pk_fma_f32 v[20:21], v[6:7], v[96:97], v[20:21]
	v_pk_fma_f32 v[22:23], v[14:15], v[96:97], v[22:23]
	v_add_f32_e32 v26, v20, v21
	v_add_f32_e32 v27, v22, v23
	v_pk_fma_f32 v[178:179], v[24:25], v[142:143], v[26:27] op_sel_hi:[1,0,1]
	v_pk_mul_f32 v[164:165], v[112:113], v[24:25] op_sel_hi:[1,0]
	v_pk_mul_f32 v[166:167], v[112:113], v[24:25] op_sel:[0,1]
	v_pk_mul_f32 v[168:169], v[114:115], v[24:25] op_sel_hi:[1,0]
	v_pk_mul_f32 v[170:171], v[114:115], v[24:25] op_sel:[0,1]
	v_pk_fma_f32 v[164:165], v[120:121], v[74:75], v[164:165] op_sel_hi:[1,0,1]
	v_pk_fma_f32 v[166:167], v[120:121], v[74:75], v[166:167] op_sel:[0,1,0]
	v_pk_fma_f32 v[168:169], v[122:123], v[74:75], v[168:169] op_sel_hi:[1,0,1]
	v_pk_fma_f32 v[170:171], v[122:123], v[74:75], v[170:171] op_sel:[0,1,0]
	v_pk_fma_f32 v[0:1], v[0:1], v[98:99], v[164:165]
	v_pk_fma_f32 v[8:9], v[8:9], v[98:99], v[166:167]
	v_pk_fma_f32 v[2:3], v[2:3], v[100:101], v[168:169]
	v_pk_fma_f32 v[10:11], v[10:11], v[100:101], v[170:171]
	v_pk_mul_f32 v[164:165], v[116:117], v[24:25] op_sel_hi:[1,0]
	v_pk_mul_f32 v[166:167], v[116:117], v[24:25] op_sel:[0,1]
	v_pk_mul_f32 v[168:169], v[118:119], v[24:25] op_sel_hi:[1,0]
	v_pk_mul_f32 v[170:171], v[118:119], v[24:25] op_sel:[0,1]
	v_pk_fma_f32 v[164:165], v[124:125], v[74:75], v[164:165] op_sel_hi:[1,0,1]
	v_pk_fma_f32 v[166:167], v[124:125], v[74:75], v[166:167] op_sel:[0,1,0]
	v_pk_fma_f32 v[168:169], v[126:127], v[74:75], v[168:169] op_sel_hi:[1,0,1]
	v_pk_fma_f32 v[170:171], v[126:127], v[74:75], v[170:171] op_sel:[0,1,0]
	v_pk_fma_f32 v[4:5], v[4:5], v[102:103], v[164:165]
	v_pk_fma_f32 v[12:13], v[12:13], v[102:103], v[166:167]
	v_pk_fma_f32 v[6:7], v[6:7], v[104:105], v[168:169]
	v_pk_fma_f32 v[14:15], v[14:15], v[104:105], v[170:171]
	v_pk_fma_f32 v[178:179], v[74:75], v[142:143], v[178:179] op_sel:[0,1,0]
	s_waitcnt lgkmcnt(0)
	v_pk_mul_f32 v[16:17], v[2:3], v[34:35]
	v_pk_mul_f32 v[18:19], v[10:11], v[34:35]
	ds_read_b128 v[76:79], v130 offset:768
	v_pk_fma_f32 v[16:17], v[0:1], v[32:33], v[16:17]
	v_pk_fma_f32 v[18:19], v[8:9], v[32:33], v[18:19]
	ds_read_b128 v[80:83], v130 offset:784
	v_pk_fma_f32 v[16:17], v[4:5], v[36:37], v[16:17]
	v_pk_fma_f32 v[18:19], v[12:13], v[36:37], v[18:19]
	ds_read_b128 v[90:93], v130 offset:4864
	v_pk_fma_f32 v[16:17], v[6:7], v[38:39], v[16:17]
	v_pk_fma_f32 v[18:19], v[14:15], v[38:39], v[18:19]
	ds_read_b128 v[94:97], v130 offset:4880
	v_pk_mul_f32 v[20:21], v[2:3], v[42:43]
	v_add_f32_e32 v24, v16, v17
	ds_read_b128 v[112:115], v130 offset:13056
	v_add_f32_e32 v25, v18, v19
	v_pk_mul_f32 v[22:23], v[10:11], v[42:43]
	ds_read_b128 v[116:119], v130 offset:13072
	v_add_f32_dpp v24, v24, v24 quad_perm:[1,0,3,2] row_mask:0xf bank_mask:0xf bound_ctrl:1
	v_add_f32_dpp v25, v25, v25 quad_perm:[1,0,3,2] row_mask:0xf bank_mask:0xf bound_ctrl:1
	ds_read_b128 v[120:123], v130 offset:17152
	v_pk_fma_f32 v[20:21], v[0:1], v[40:41], v[20:21]
	v_add_f32_dpp v24, v24, v24 quad_perm:[2,3,0,1] row_mask:0xf bank_mask:0xf bound_ctrl:1
	ds_read_b128 v[124:127], v130 offset:17168
	v_add_f32_dpp v25, v25, v25 quad_perm:[2,3,0,1] row_mask:0xf bank_mask:0xf bound_ctrl:1
	v_pk_fma_f32 v[22:23], v[8:9], v[40:41], v[22:23]
	ds_read_b128 v[98:101], v130 offset:8960
	v_add_f32_dpp v24, v24, v24 row_half_mirror row_mask:0xf bank_mask:0xf bound_ctrl:1
	v_add_f32_dpp v25, v25, v25 row_half_mirror row_mask:0xf bank_mask:0xf bound_ctrl:1
	ds_read_b128 v[102:105], v130 offset:8976
	v_pk_fma_f32 v[20:21], v[4:5], v[44:45], v[20:21]
	v_pk_fma_f32 v[22:23], v[12:13], v[44:45], v[22:23]
	ds_read2_b64 v[72:75], v131 offset0:128 offset1:160
	v_pk_fma_f32 v[20:21], v[6:7], v[46:47], v[20:21]
	v_pk_fma_f32 v[22:23], v[14:15], v[46:47], v[22:23]
	ds_read2_b64 v[140:143], v85 offset0:8 offset1:10
	v_add_f32_e32 v26, v20, v21
	v_add_f32_e32 v27, v22, v23
	v_pk_fma_f32 v[180:181], v[24:25], v[144:145], v[26:27] op_sel_hi:[1,0,1]
	v_pk_mul_f32 v[164:165], v[56:57], v[24:25] op_sel_hi:[1,0]
	v_pk_mul_f32 v[166:167], v[56:57], v[24:25] op_sel:[0,1]
	v_pk_mul_f32 v[168:169], v[58:59], v[24:25] op_sel_hi:[1,0]
	v_pk_mul_f32 v[170:171], v[58:59], v[24:25] op_sel:[0,1]
	v_pk_fma_f32 v[164:165], v[64:65], v[106:107], v[164:165] op_sel_hi:[1,0,1]
	v_pk_fma_f32 v[166:167], v[64:65], v[106:107], v[166:167] op_sel:[0,1,0]
	v_pk_fma_f32 v[168:169], v[66:67], v[106:107], v[168:169] op_sel_hi:[1,0,1]
	v_pk_fma_f32 v[170:171], v[66:67], v[106:107], v[170:171] op_sel:[0,1,0]
	v_pk_fma_f32 v[0:1], v[0:1], v[48:49], v[164:165]
	v_pk_fma_f32 v[8:9], v[8:9], v[48:49], v[166:167]
	v_pk_fma_f32 v[2:3], v[2:3], v[50:51], v[168:169]
	v_pk_fma_f32 v[10:11], v[10:11], v[50:51], v[170:171]
	v_pk_mul_f32 v[164:165], v[60:61], v[24:25] op_sel_hi:[1,0]
	v_pk_mul_f32 v[166:167], v[60:61], v[24:25] op_sel:[0,1]
	v_pk_mul_f32 v[168:169], v[62:63], v[24:25] op_sel_hi:[1,0]
	v_pk_mul_f32 v[170:171], v[62:63], v[24:25] op_sel:[0,1]
	v_pk_fma_f32 v[164:165], v[68:69], v[106:107], v[164:165] op_sel_hi:[1,0,1]
	v_pk_fma_f32 v[166:167], v[68:69], v[106:107], v[166:167] op_sel:[0,1,0]
	v_pk_fma_f32 v[168:169], v[70:71], v[106:107], v[168:169] op_sel_hi:[1,0,1]
	v_pk_fma_f32 v[170:171], v[70:71], v[106:107], v[170:171] op_sel:[0,1,0]
	v_pk_fma_f32 v[4:5], v[4:5], v[52:53], v[164:165]
	v_pk_fma_f32 v[12:13], v[12:13], v[52:53], v[166:167]
	v_pk_fma_f32 v[6:7], v[6:7], v[54:55], v[168:169]
	v_pk_fma_f32 v[14:15], v[14:15], v[54:55], v[170:171]
	v_pk_fma_f32 v[180:181], v[106:107], v[144:145], v[180:181] op_sel:[0,1,0]
	s_waitcnt lgkmcnt(0)
	v_pk_mul_f32 v[16:17], v[2:3], v[78:79]
	v_pk_mul_f32 v[18:19], v[10:11], v[78:79]
	ds_read_b128 v[32:35], v130 offset:1024
	v_pk_fma_f32 v[16:17], v[0:1], v[76:77], v[16:17]
	v_pk_fma_f32 v[18:19], v[8:9], v[76:77], v[18:19]
	ds_read_b128 v[36:39], v130 offset:1040
	v_pk_fma_f32 v[16:17], v[4:5], v[80:81], v[16:17]
	v_pk_fma_f32 v[18:19], v[12:13], v[80:81], v[18:19]
	ds_read_b128 v[40:43], v130 offset:5120
	v_pk_fma_f32 v[16:17], v[6:7], v[82:83], v[16:17]
	v_pk_fma_f32 v[18:19], v[14:15], v[82:83], v[18:19]
	ds_read_b128 v[44:47], v130 offset:5136
	v_pk_mul_f32 v[20:21], v[2:3], v[92:93]
	v_add_f32_e32 v24, v16, v17
	ds_read_b128 v[56:59], v130 offset:13312
	v_add_f32_e32 v25, v18, v19
	v_pk_mul_f32 v[22:23], v[10:11], v[92:93]
	ds_read_b128 v[60:63], v130 offset:13328
	v_add_f32_dpp v24, v24, v24 quad_perm:[1,0,3,2] row_mask:0xf bank_mask:0xf bound_ctrl:1
	v_add_f32_dpp v25, v25, v25 quad_perm:[1,0,3,2] row_mask:0xf bank_mask:0xf bound_ctrl:1
	ds_read_b128 v[64:67], v130 offset:17408
	v_pk_fma_f32 v[20:21], v[0:1], v[90:91], v[20:21]
	v_add_f32_dpp v24, v24, v24 quad_perm:[2,3,0,1] row_mask:0xf bank_mask:0xf bound_ctrl:1
	ds_read_b128 v[68:71], v130 offset:17424
	v_add_f32_dpp v25, v25, v25 quad_perm:[2,3,0,1] row_mask:0xf bank_mask:0xf bound_ctrl:1
	v_pk_fma_f32 v[22:23], v[8:9], v[90:91], v[22:23]
	ds_read_b128 v[48:51], v130 offset:9216
	v_add_f32_dpp v24, v24, v24 row_half_mirror row_mask:0xf bank_mask:0xf bound_ctrl:1
	v_add_f32_dpp v25, v25, v25 row_half_mirror row_mask:0xf bank_mask:0xf bound_ctrl:1
	ds_read_b128 v[52:55], v130 offset:9232
	v_pk_fma_f32 v[20:21], v[4:5], v[94:95], v[20:21]
	v_pk_fma_f32 v[22:23], v[12:13], v[94:95], v[22:23]
	v_pk_fma_f32 v[20:21], v[6:7], v[96:97], v[20:21]
	v_pk_fma_f32 v[22:23], v[14:15], v[96:97], v[22:23]
	v_add_f32_e32 v26, v20, v21
	v_add_f32_e32 v27, v22, v23
	v_pk_fma_f32 v[182:183], v[24:25], v[146:147], v[26:27] op_sel_hi:[1,0,1]
	v_pk_mul_f32 v[164:165], v[112:113], v[24:25] op_sel_hi:[1,0]
	v_pk_mul_f32 v[166:167], v[112:113], v[24:25] op_sel:[0,1]
	v_pk_mul_f32 v[168:169], v[114:115], v[24:25] op_sel_hi:[1,0]
	v_pk_mul_f32 v[170:171], v[114:115], v[24:25] op_sel:[0,1]
	v_pk_fma_f32 v[164:165], v[120:121], v[108:109], v[164:165] op_sel_hi:[1,0,1]
	v_pk_fma_f32 v[166:167], v[120:121], v[108:109], v[166:167] op_sel:[0,1,0]
	v_pk_fma_f32 v[168:169], v[122:123], v[108:109], v[168:169] op_sel_hi:[1,0,1]
	v_pk_fma_f32 v[170:171], v[122:123], v[108:109], v[170:171] op_sel:[0,1,0]
	v_pk_fma_f32 v[0:1], v[0:1], v[98:99], v[164:165]
	v_pk_fma_f32 v[8:9], v[8:9], v[98:99], v[166:167]
	v_pk_fma_f32 v[2:3], v[2:3], v[100:101], v[168:169]
	v_pk_fma_f32 v[10:11], v[10:11], v[100:101], v[170:171]
	v_pk_mul_f32 v[164:165], v[116:117], v[24:25] op_sel_hi:[1,0]
	v_pk_mul_f32 v[166:167], v[116:117], v[24:25] op_sel:[0,1]
	v_pk_mul_f32 v[168:169], v[118:119], v[24:25] op_sel_hi:[1,0]
	v_pk_mul_f32 v[170:171], v[118:119], v[24:25] op_sel:[0,1]
	v_pk_fma_f32 v[164:165], v[124:125], v[108:109], v[164:165] op_sel_hi:[1,0,1]
	v_pk_fma_f32 v[166:167], v[124:125], v[108:109], v[166:167] op_sel:[0,1,0]
	v_pk_fma_f32 v[168:169], v[126:127], v[108:109], v[168:169] op_sel_hi:[1,0,1]
	v_pk_fma_f32 v[170:171], v[126:127], v[108:109], v[170:171] op_sel:[0,1,0]
	v_pk_fma_f32 v[4:5], v[4:5], v[102:103], v[164:165]
	v_pk_fma_f32 v[12:13], v[12:13], v[102:103], v[166:167]
	v_pk_fma_f32 v[6:7], v[6:7], v[104:105], v[168:169]
	v_pk_fma_f32 v[14:15], v[14:15], v[104:105], v[170:171]
	v_pk_fma_f32 v[182:183], v[108:109], v[146:147], v[182:183] op_sel:[0,1,0]
	v_add_f32_dpp v176, v176, v176 row_half_mirror row_mask:0xf bank_mask:0x5
	v_add_f32_dpp v176, v180, v180 row_half_mirror row_mask:0xf bank_mask:0xa
	v_add_f32_dpp v177, v177, v177 row_half_mirror row_mask:0xf bank_mask:0x5
	v_add_f32_dpp v177, v181, v181 row_half_mirror row_mask:0xf bank_mask:0xa
	v_add_f32_dpp v178, v178, v178 row_half_mirror row_mask:0xf bank_mask:0x5
	v_add_f32_dpp v178, v182, v182 row_half_mirror row_mask:0xf bank_mask:0xa
	v_add_f32_dpp v179, v179, v179 row_half_mirror row_mask:0xf bank_mask:0x5
	v_add_f32_dpp v179, v183, v183 row_half_mirror row_mask:0xf bank_mask:0xa
	v_cndmask_b32_e64 v16, v178, v176, s[46:47]
	v_cndmask_b32_e64 v17, v176, v178, s[46:47]
	v_cndmask_b32_e64 v18, v179, v177, s[46:47]
	v_cndmask_b32_e64 v19, v177, v179, s[46:47]
	v_add_u32_e32 v130, 0x400, v130
	v_add_f32_dpp v176, v17, v16 quad_perm:[2,3,0,1] row_mask:0xf bank_mask:0xf bound_ctrl:1
	v_add_u32_e32 v131, 0x400, v131
	v_add_f32_dpp v177, v19, v18 quad_perm:[2,3,0,1] row_mask:0xf bank_mask:0xf bound_ctrl:1
	v_add_u32_e32 v85, 64, v85
	v_cndmask_b32_e64 v16, v177, v176, s[48:49]
	v_cndmask_b32_e64 v17, v176, v177, s[48:49]
	s_add_i32 s0, s0, -1
	s_cmp_lg_u32 s0, 0
	v_add_f32_dpp v18, v17, v16 quad_perm:[1,0,3,2] row_mask:0xf bank_mask:0xf bound_ctrl:1
	s_nop 0
	ds_write_b32 v86, v18
	v_add_u32_e32 v86, 0x400, v86
	s_cbranch_scc1 .Lscan_q4
	s_xor_b32 s1, s1, 0x8200
	s_add_i32 s2, s2, -1
	s_waitcnt lgkmcnt(0)
	s_barrier
	s_cmp_lg_u32 s2, 0
	s_cbranch_scc1 .Lscan_chunk
	s_branch .LBB0_627
